# dilated merge: batch 8 prev-output loads with lse load (1 round trip instead of 9)
# baseline (speedup 1.0000x reference)
.LBB0_760:
	s_or_b64 exec, exec, s[34:35]
	s_ashr_i32 s0, s78, 31
	s_lshr_b32 s0, s0, 28
	s_add_i32 s1, s78, s0
	s_ashr_i32 s2, s1, 4
	s_abs_i32 s3, s2
	s_mul_hi_u32 s4, s3, s73
	s_mul_i32 s5, s4, s40
	ds_bpermute_b32 v1, v145, v147
	s_sub_i32 s3, s3, s5
	s_ashr_i32 s0, s1, 31
	s_add_i32 s5, s4, 1
	s_sub_i32 s6, s3, s40
	s_cmp_ge_u32 s3, s40
	s_cselect_b32 s4, s5, s4
	s_cselect_b32 s3, s6, s3
	s_add_i32 s5, s4, 1
	s_waitcnt lgkmcnt(0)
	v_add_f32_e32 v5, v147, v1
	s_cmp_ge_u32 s3, s40
	v_cmp_gt_f32_e32 vcc, s95, v5
	s_cselect_b32 s3, s5, s4
	s_xor_b32 s3, s3, s0
	v_cndmask_b32_e64 v1, 0, 32, vcc
	v_ldexp_f32 v1, v5, v1
	s_sub_i32 s0, s3, s0
	v_log_f32_e32 v1, v1
	s_mul_i32 s3, s0, s40
	s_and_b32 s1, s1, -16
	s_sub_i32 s3, s2, s3
	s_sub_i32 s2, s78, s1
	v_mov_b32_e32 v2, 0x42000000
	s_ashr_i32 s1, s0, 31
	v_cndmask_b32_e32 v2, 0, v2, vcc
	s_lshl_b64 s[0:1], s[0:1], 13
	s_ashr_i32 s4, s3, 31
	v_sub_f32_e32 v1, v1, v2
	v_ashrrev_i32_e32 v147, 31, v146
	s_add_u32 s0, s0, s3
	v_add_f32_e32 v1, v148, v1
	v_lshlrev_b64 v[2:3], s71, v[146:147]
	s_addc_u32 s1, s1, s4
	v_cndmask_b32_e64 v6, 0, 1, s[24:25]
	v_mov_b32_e32 v4, 0
	v_mul_f32_e32 v1, 0x3f317218, v1
	v_lshl_add_u64 v[2:3], s[0:1], 0, v[2:3]
	v_cmp_ne_u32_e64 s[0:1], 1, v6
	s_andn2_b64 vcc, exec, s[24:25]
	v_mov_b32_e32 v6, 1.0
	s_cbranch_vccnz .LBB0_762
	v_lshlrev_b64 v[6:7], 6, v[2:3]
	s_ashr_i32 s3, s2, 31
	v_lshl_add_u64 v[6:7], s[28:29], 0, v[6:7]
	v_lshl_add_u64 v[6:7], s[2:3], 2, v[6:7]
	global_load_dword v4, v[6:7], off
	v_lshlrev_b64 v[220:221], 11, v[2:3]
	s_lshl_b32 s4, s2, 6
	v_lshl_add_u64 v[220:221], s[26:27], 0, v[220:221]
	s_ashr_i32 s5, s4, 31
	v_lshlrev_b32_e32 v222, 1, v144
	v_lshl_add_u64 v[220:221], s[4:5], 1, v[220:221]
	v_mad_u64_u32 v[220:221], vcc, v222, 1, v[220:221]
	global_load_dwordx2 v[236:237], v[220:221], off
	global_load_dwordx2 v[238:239], v[220:221], off offset:16
	global_load_dwordx2 v[240:241], v[220:221], off offset:32
	global_load_dwordx2 v[242:243], v[220:221], off offset:48
	global_load_dwordx2 v[244:245], v[220:221], off offset:64
	global_load_dwordx2 v[246:247], v[220:221], off offset:80
	global_load_dwordx2 v[248:249], v[220:221], off offset:96
	global_load_dwordx2 v[250:251], v[220:221], off offset:112
	v_max_f32_e32 v6, v1, v1
	s_mov_b32 s3, 0x3f317217
	s_waitcnt vmcnt(0)
	v_max_f32_e32 v7, v4, v4
	v_max_f32_e32 v6, v7, v6
	v_sub_f32_e32 v7, v4, v6
	v_sub_f32_e32 v8, v1, v6
	v_mul_f32_e32 v7, 0x3fb8aa3b, v7
	v_mul_f32_e32 v8, 0x3fb8aa3b, v8
	v_exp_f32_e32 v7, v7
	v_exp_f32_e32 v8, v8
	s_nop 0
	v_add_f32_e32 v7, v7, v8
	v_cmp_gt_f32_e32 vcc, s95, v7
	s_nop 1
	v_cndmask_b32_e64 v8, 0, 32, vcc
	v_ldexp_f32 v7, v7, v8
	v_log_f32_e32 v7, v7
	v_mov_b32_e32 v8, 0x41b17218
	v_cndmask_b32_e32 v8, 0, v8, vcc
	v_mul_f32_e32 v9, 0x3f317217, v7
	v_fma_f32 v9, v7, s3, -v9
	v_fmac_f32_e32 v9, 0x3377d1cf, v7
	s_mov_b32 s3, 0x7f800000
	v_fmac_f32_e32 v9, 0x3f317217, v7
	v_cmp_lt_f32_e64 vcc, |v7|, s3
	s_nop 1
	v_cndmask_b32_e32 v7, v7, v9, vcc
	v_sub_f32_e32 v7, v7, v8
	v_add_f32_e32 v7, v6, v7
	v_sub_f32_e32 v4, v4, v7
	v_sub_f32_e32 v1, v1, v7
	v_mul_f32_e32 v4, 0x3fb8aa3b, v4
	v_mul_f32_e32 v1, 0x3fb8aa3b, v1
	v_exp_f32_e32 v4, v4
	v_exp_f32_e32 v6, v1
	v_mov_b32_e32 v1, v7
.LBB0_762:
	v_div_scale_f32 v7, s[4:5], v5, v5, 1.0
	v_rcp_f32_e32 v8, v7
	v_div_scale_f32 v9, vcc, 1.0, v5, 1.0
	s_lshl_b32 s4, s2, 6
	v_fma_f32 v10, -v7, v8, 1.0
	v_fmac_f32_e32 v8, v10, v8
	v_mul_f32_e32 v10, v9, v8
	v_fma_f32 v11, -v7, v10, v9
	v_fmac_f32_e32 v10, v11, v8
	v_fma_f32 v7, -v7, v10, v9
	v_div_fmas_f32 v7, v7, v8, v10
	v_div_fixup_f32 v8, v7, v5, 1.0
	v_lshlrev_b64 v[10:11], 11, v[2:3]
	v_pk_mul_f32 v[12:13], v[32:33], v[8:9] op_sel_hi:[1,0]
	v_lshl_add_u64 v[10:11], s[26:27], 0, v[10:11]
	s_ashr_i32 s5, s4, 31
	v_pk_mul_f32 v[14:15], v[12:13], v[6:7] op_sel_hi:[1,0]
	v_pk_mul_f32 v[12:13], v[34:35], v[8:9] op_sel_hi:[1,0]
	v_lshl_add_u64 v[10:11], s[4:5], 1, v[10:11]
	v_pk_mul_f32 v[32:33], v[12:13], v[6:7] op_sel_hi:[1,0]
	s_and_b64 vcc, exec, s[0:1]
	v_lshlrev_b32_e32 v12, 1, v144
	s_cbranch_vccnz .LBB0_764
	v_mov_b32_e32 v13, v0
	v_lshl_add_u64 v[34:35], v[10:11], 0, v[12:13]
	v_mov_b32_e32 v34, v236
	v_mov_b32_e32 v35, v237
	v_lshlrev_b32_e32 v48, 16, v34
	v_and_b32_e32 v49, 0xffff0000, v34
	v_lshlrev_b32_e32 v34, 16, v35
	v_and_b32_e32 v35, 0xffff0000, v35
	v_pk_fma_f32 v[14:15], v[4:5], v[48:49], v[14:15] op_sel_hi:[0,1,1]
	v_pk_fma_f32 v[32:33], v[4:5], v[34:35], v[32:33] op_sel_hi:[0,1,1]
.LBB0_764:
	v_mov_b32_e32 v13, v0
	v_mov_b32_e32 v9, v8
	v_cvt_pk_bf16_f32 v14, v14, v15
	v_cvt_pk_bf16_f32 v15, v32, v33
	v_lshl_add_u64 v[10:11], v[10:11], 0, v[12:13]
	v_mov_b32_e32 v7, v6
	global_store_dwordx2 v[10:11], v[14:15], off
	v_pk_mul_f32 v[12:13], v[36:37], v[8:9]
	v_pk_mul_f32 v[14:15], v[38:39], v[8:9]
	v_pk_mul_f32 v[12:13], v[12:13], v[6:7]
	s_and_b64 vcc, exec, s[0:1]
	v_pk_mul_f32 v[14:15], v[14:15], v[6:7]
	s_cbranch_vccnz .LBB0_766
	v_mov_b32_e32 v32, v238
	v_mov_b32_e32 v33, v239
	v_lshlrev_b32_e32 v34, 16, v32
	v_and_b32_e32 v35, 0xffff0000, v32
	v_lshlrev_b32_e32 v32, 16, v33
	v_and_b32_e32 v33, 0xffff0000, v33
	v_pk_fma_f32 v[12:13], v[4:5], v[34:35], v[12:13] op_sel_hi:[0,1,1]
	v_pk_fma_f32 v[14:15], v[4:5], v[32:33], v[14:15] op_sel_hi:[0,1,1]
.LBB0_766:
	v_cvt_pk_bf16_f32 v12, v12, v13
	v_cvt_pk_bf16_f32 v13, v14, v15
	global_store_dwordx2 v[10:11], v[12:13], off offset:16
	v_pk_mul_f32 v[12:13], v[40:41], v[8:9]
	v_pk_mul_f32 v[14:15], v[42:43], v[8:9]
	v_pk_mul_f32 v[12:13], v[12:13], v[6:7]
	s_and_b64 vcc, exec, s[0:1]
	v_pk_mul_f32 v[14:15], v[14:15], v[6:7]
	s_cbranch_vccnz .LBB0_768
	v_mov_b32_e32 v32, v240
	v_mov_b32_e32 v33, v241
	v_lshlrev_b32_e32 v34, 16, v32
	v_and_b32_e32 v35, 0xffff0000, v32
	v_lshlrev_b32_e32 v32, 16, v33
	v_and_b32_e32 v33, 0xffff0000, v33
	v_pk_fma_f32 v[12:13], v[4:5], v[34:35], v[12:13] op_sel_hi:[0,1,1]
	v_pk_fma_f32 v[14:15], v[4:5], v[32:33], v[14:15] op_sel_hi:[0,1,1]
.LBB0_768:
	v_cvt_pk_bf16_f32 v12, v12, v13
	v_cvt_pk_bf16_f32 v13, v14, v15
	global_store_dwordx2 v[10:11], v[12:13], off offset:32
	v_pk_mul_f32 v[12:13], v[44:45], v[8:9]
	v_pk_mul_f32 v[14:15], v[46:47], v[8:9]
	v_pk_mul_f32 v[12:13], v[12:13], v[6:7]
	s_and_b64 vcc, exec, s[0:1]
	v_pk_mul_f32 v[14:15], v[14:15], v[6:7]
	s_cbranch_vccnz .LBB0_770
	v_mov_b32_e32 v32, v242
	v_mov_b32_e32 v33, v243
	v_lshlrev_b32_e32 v34, 16, v32
	v_and_b32_e32 v35, 0xffff0000, v32
	v_lshlrev_b32_e32 v32, 16, v33
	v_and_b32_e32 v33, 0xffff0000, v33
	v_pk_fma_f32 v[12:13], v[4:5], v[34:35], v[12:13] op_sel_hi:[0,1,1]
	v_pk_fma_f32 v[14:15], v[4:5], v[32:33], v[14:15] op_sel_hi:[0,1,1]
.LBB0_770:
	v_cvt_pk_bf16_f32 v12, v12, v13
	v_cvt_pk_bf16_f32 v13, v14, v15
	global_store_dwordx2 v[10:11], v[12:13], off offset:48
	v_pk_mul_f32 v[12:13], v[16:17], v[8:9]
	v_pk_mul_f32 v[14:15], v[18:19], v[8:9]
	v_pk_mul_f32 v[12:13], v[12:13], v[6:7]
	s_and_b64 vcc, exec, s[0:1]
	v_pk_mul_f32 v[14:15], v[14:15], v[6:7]
	s_cbranch_vccnz .LBB0_772
	v_mov_b32_e32 v16, v244
	v_mov_b32_e32 v17, v245
	v_lshlrev_b32_e32 v18, 16, v16
	v_and_b32_e32 v19, 0xffff0000, v16
	v_lshlrev_b32_e32 v16, 16, v17
	v_and_b32_e32 v17, 0xffff0000, v17
	v_pk_fma_f32 v[12:13], v[4:5], v[18:19], v[12:13] op_sel_hi:[0,1,1]
	v_pk_fma_f32 v[14:15], v[4:5], v[16:17], v[14:15] op_sel_hi:[0,1,1]
.LBB0_772:
	v_cvt_pk_bf16_f32 v12, v12, v13
	v_cvt_pk_bf16_f32 v13, v14, v15
	global_store_dwordx2 v[10:11], v[12:13], off offset:64
	v_pk_mul_f32 v[12:13], v[20:21], v[8:9]
	v_pk_mul_f32 v[14:15], v[22:23], v[8:9]
	v_pk_mul_f32 v[12:13], v[12:13], v[6:7]
	s_and_b64 vcc, exec, s[0:1]
	v_pk_mul_f32 v[14:15], v[14:15], v[6:7]
	s_cbranch_vccnz .LBB0_774
	v_mov_b32_e32 v16, v246
	v_mov_b32_e32 v17, v247
	v_lshlrev_b32_e32 v18, 16, v16
	v_and_b32_e32 v19, 0xffff0000, v16
	v_lshlrev_b32_e32 v16, 16, v17
	v_and_b32_e32 v17, 0xffff0000, v17
	v_pk_fma_f32 v[12:13], v[4:5], v[18:19], v[12:13] op_sel_hi:[0,1,1]
	v_pk_fma_f32 v[14:15], v[4:5], v[16:17], v[14:15] op_sel_hi:[0,1,1]
.LBB0_774:
	v_cvt_pk_bf16_f32 v12, v12, v13
	v_cvt_pk_bf16_f32 v13, v14, v15
	global_store_dwordx2 v[10:11], v[12:13], off offset:80
	v_pk_mul_f32 v[12:13], v[24:25], v[8:9]
	v_pk_mul_f32 v[14:15], v[26:27], v[8:9]
	v_pk_mul_f32 v[12:13], v[12:13], v[6:7]
	s_and_b64 vcc, exec, s[0:1]
	v_pk_mul_f32 v[14:15], v[14:15], v[6:7]
	s_cbranch_vccnz .LBB0_776
	v_mov_b32_e32 v16, v248
	v_mov_b32_e32 v17, v249
	v_lshlrev_b32_e32 v18, 16, v16
	v_and_b32_e32 v19, 0xffff0000, v16
	v_lshlrev_b32_e32 v16, 16, v17
	v_and_b32_e32 v17, 0xffff0000, v17
	v_pk_fma_f32 v[12:13], v[4:5], v[18:19], v[12:13] op_sel_hi:[0,1,1]
	v_pk_fma_f32 v[14:15], v[4:5], v[16:17], v[14:15] op_sel_hi:[0,1,1]
.LBB0_776:
	v_cvt_pk_bf16_f32 v12, v12, v13
	v_cvt_pk_bf16_f32 v13, v14, v15
	global_store_dwordx2 v[10:11], v[12:13], off offset:96
	v_pk_mul_f32 v[12:13], v[28:29], v[8:9]
	v_pk_mul_f32 v[8:9], v[30:31], v[8:9]
	v_pk_mul_f32 v[12:13], v[12:13], v[6:7]
	s_and_b64 vcc, exec, s[0:1]
	v_pk_mul_f32 v[6:7], v[8:9], v[6:7]
	s_cbranch_vccnz .LBB0_778
	v_mov_b32_e32 v8, v250
	v_mov_b32_e32 v9, v251
	v_lshlrev_b32_e32 v14, 16, v8
	v_and_b32_e32 v15, 0xffff0000, v8
	v_lshlrev_b32_e32 v8, 16, v9
	v_and_b32_e32 v9, 0xffff0000, v9
	v_pk_fma_f32 v[12:13], v[4:5], v[14:15], v[12:13] op_sel_hi:[0,1,1]
	v_pk_fma_f32 v[6:7], v[4:5], v[8:9], v[6:7] op_sel_hi:[0,1,1]
